# context-row norm phases after a split-K residual GEMM: the 16 partial-sum loads of a row issued together (were 16 dependent round trips)
# baseline (speedup 1.0000x reference)
; __device__ __forceinline__ void norm_phase(const float* xs_lat, const float* xs_ctx, const float* partA, const float* partB, float* xc_wr, int row_begin, int rows, const float* gain, const float* modl, int shoff, int scoff, bf16_t* H, int gw, int NGW, int lane) {
;     ...
;             if (!lat && partA != nullptr) {
;                 const size_t ro = (size_t)(row - ML) * D;
; #pragma unroll
;                 for (int j = 0; j < 4; ++j) { const int ix = 64 * j + lane;
;                     v[u][j] = (((v[u][j] + ((const f32x4*)(partA + ro))[ix]) + ((const f32x4*)(partA + (size_t)MC * D + ro))[ix]) + ((const f32x4*)(partB + ro))[ix]) + ((const f32x4*)(partB + (size_t)MC * D + ro))[ix];
;                     ((f32x4*)(xc_wr + ro))[ix] = v[u][j]; }
;             }
.LBB0_1162:
	s_or_b64 s[4:5], s[10:11], s[42:43]
	s_and_b64 vcc, exec, s[4:5]
	s_cbranch_vccnz .LBB0_1164
	s_lshl_b64 s[4:5], s[34:35], 12
	v_lshl_add_u64 v[68:69], v[42:43], 0, s[4:5]
	v_lshl_add_u64 v[70:71], v[44:45], 0, s[4:5]
	v_lshl_add_u64 v[72:73], v[46:47], 0, s[4:5]
	v_lshl_add_u64 v[74:75], v[48:49], 0, s[4:5]
	v_lshl_add_u64 v[76:77], v[50:51], 0, s[4:5]
	global_load_dwordx4 v[132:135], v[68:69], off
	global_load_dwordx4 v[136:139], v[70:71], off
	global_load_dwordx4 v[140:143], v[72:73], off
	global_load_dwordx4 v[144:147], v[74:75], off
	global_load_dwordx4 v[148:151], v[68:69], off offset:1024
	global_load_dwordx4 v[152:155], v[70:71], off offset:1024
	global_load_dwordx4 v[160:163], v[72:73], off offset:1024
	global_load_dwordx4 v[164:167], v[74:75], off offset:1024
	global_load_dwordx4 v[168:171], v[68:69], off offset:2048
	global_load_dwordx4 v[208:211], v[70:71], off offset:2048
	global_load_dwordx4 v[212:215], v[72:73], off offset:2048
	global_load_dwordx4 v[226:229], v[74:75], off offset:2048
	global_load_dwordx4 v[230:233], v[68:69], off offset:3072
	global_load_dwordx4 v[234:237], v[70:71], off offset:3072
	global_load_dwordx4 v[238:241], v[72:73], off offset:3072
	global_load_dwordx4 v[242:245], v[74:75], off offset:3072
	s_waitcnt vmcnt(0)
	v_pk_add_f32 v[20:21], v[20:21], v[132:133]
	v_pk_add_f32 v[22:23], v[22:23], v[134:135]
	v_pk_add_f32 v[20:21], v[20:21], v[136:137]
	v_pk_add_f32 v[22:23], v[22:23], v[138:139]
	v_pk_add_f32 v[20:21], v[20:21], v[140:141]
	v_pk_add_f32 v[22:23], v[22:23], v[142:143]
	v_pk_add_f32 v[20:21], v[20:21], v[144:145]
	v_pk_add_f32 v[22:23], v[22:23], v[146:147]
	global_store_dwordx4 v[76:77], v[20:23], off
	v_pk_add_f32 v[28:29], v[28:29], v[148:149]
	v_pk_add_f32 v[30:31], v[30:31], v[150:151]
	v_pk_add_f32 v[28:29], v[28:29], v[152:153]
	v_pk_add_f32 v[30:31], v[30:31], v[154:155]
	v_pk_add_f32 v[28:29], v[28:29], v[160:161]
	v_pk_add_f32 v[30:31], v[30:31], v[162:163]
	v_pk_add_f32 v[28:29], v[28:29], v[164:165]
	v_pk_add_f32 v[30:31], v[30:31], v[166:167]
	global_store_dwordx4 v[76:77], v[28:31], off offset:1024
	v_pk_add_f32 v[16:17], v[16:17], v[168:169]
	v_pk_add_f32 v[18:19], v[18:19], v[170:171]
	v_pk_add_f32 v[16:17], v[16:17], v[208:209]
	v_pk_add_f32 v[18:19], v[18:19], v[210:211]
	v_pk_add_f32 v[16:17], v[16:17], v[212:213]
	v_pk_add_f32 v[18:19], v[18:19], v[214:215]
	v_pk_add_f32 v[16:17], v[16:17], v[226:227]
	v_pk_add_f32 v[18:19], v[18:19], v[228:229]
	global_store_dwordx4 v[76:77], v[16:19], off offset:2048
	v_pk_add_f32 v[24:25], v[24:25], v[230:231]
	v_pk_add_f32 v[26:27], v[26:27], v[232:233]
	v_pk_add_f32 v[24:25], v[24:25], v[234:235]
	v_pk_add_f32 v[26:27], v[26:27], v[236:237]
	v_pk_add_f32 v[24:25], v[24:25], v[238:239]
	v_pk_add_f32 v[26:27], v[26:27], v[240:241]
	v_pk_add_f32 v[24:25], v[24:25], v[242:243]
	v_pk_add_f32 v[26:27], v[26:27], v[244:245]
	global_store_dwordx4 v[76:77], v[24:27], off offset:3072
